# proj/gate-up: first K-iteration peeled, its first MFMA per accumulator takes C=0; the 128 v_mov accumulator zeroing per unit removed
# baseline (speedup 1.0000x reference)
.LBB0_341:
	s_ashr_i32 s27, s26, 31
	s_lshl_b64 s[28:29], s[26:27], 20
	s_add_u32 s38, s6, s28
	s_addc_u32 s39, s7, s29
	s_and_b64 s[28:29], s[36:37], exec
	s_cselect_b32 s27, s39, s47
	s_cselect_b32 s28, s38, s46
	s_ashr_i32 s25, s24, 31
	s_lshl_b64 s[34:35], s[24:25], 20
	s_add_u32 s40, s8, s34
	s_addc_u32 s41, s9, s35
	s_and_b64 s[34:35], s[36:37], exec
	s_cselect_b32 s25, s41, s45
	s_cselect_b32 s29, s40, s44
	s_add_u32 s31, s44, 0x100
	s_addc_u32 s34, s45, 0
	s_add_u32 s44, s46, 0x80080
	s_addc_u32 s45, s47, 0
	s_mov_b32 s35, -2
	s_add_u32 s33, s44, 0xfff80080
	s_addc_u32 s43, s45, -1
	s_add_i32 s50, 0, 0x10000
	s_cmp_eq_u32 s35, 28
	s_cselect_b32 s49, s27, s43
	s_cselect_b32 s48, s28, s33
	v_add_u32_e32 v142, s50, v149
	s_cselect_b32 s47, s25, s34
	s_cselect_b32 s46, s29, s31
	s_add_i32 s33, 0, 0x14000
	ds_read_b128 v[154:157], v142
	ds_read_b128 v[168:171], v142 offset:1024
	ds_read_b128 v[172:175], v142 offset:2048
	ds_read_b128 v[176:179], v142 offset:3072
	v_add_u32_e32 v142, s33, v149
	ds_read_b128 v[180:183], v142
	ds_read_b128 v[184:187], v142 offset:1024
	ds_read_b128 v[188:191], v142 offset:2048
	ds_read_b128 v[192:195], v142 offset:3072
	s_add_i32 m0, s12, 0xc000
	ds_read_b128 v[196:199], v167
	ds_read_b128 v[200:203], v167 offset:1024
	ds_read_b128 v[204:207], v167 offset:2048
	ds_read_b128 v[208:211], v167 offset:3072
	ds_read_b128 v[212:215], v167 offset:4096
	ds_read_b128 v[216:219], v167 offset:5120
	ds_read_b128 v[220:223], v167 offset:6144
	ds_read_b128 v[224:227], v167 offset:7168
	global_load_lds_dwordx4 v140, s[44:45]
	s_add_i32 m0, s12, 0xe000
	s_nop 0
	global_load_lds_dwordx4 v138, s[44:45]
	s_cmp_lg_u32 s32, 0
	s_cbranch_scc1 .Lpj_skip1_p
	s_waitcnt vmcnt(8)
.Lpj_skip1_p:
	s_waitcnt lgkmcnt(0)
	s_barrier
	s_setprio 1
	s_waitcnt lgkmcnt(0)
	v_mfma_f32_16x16x32_bf16 v[128:131], v[154:157], v[196:199], 0
	v_mfma_f32_16x16x32_bf16 v[124:127], v[172:175], v[196:199], 0
	v_mfma_f32_16x16x32_bf16 v[116:119], v[154:157], v[204:207], 0
	v_mfma_f32_16x16x32_bf16 v[108:111], v[172:175], v[204:207], 0
	v_mfma_f32_16x16x32_bf16 v[100:103], v[154:157], v[212:215], 0
	v_mfma_f32_16x16x32_bf16 v[92:95], v[172:175], v[212:215], 0
	v_mfma_f32_16x16x32_bf16 v[84:87], v[154:157], v[220:223], 0
	v_mfma_f32_16x16x32_bf16 v[76:79], v[172:175], v[220:223], 0
	v_mfma_f32_16x16x32_bf16 v[128:131], v[168:171], v[200:203], v[128:131]
	v_mfma_f32_16x16x32_bf16 v[124:127], v[176:179], v[200:203], v[124:127]
	v_mfma_f32_16x16x32_bf16 v[116:119], v[168:171], v[208:211], v[116:119]
	v_mfma_f32_16x16x32_bf16 v[108:111], v[176:179], v[208:211], v[108:111]
	v_mfma_f32_16x16x32_bf16 v[100:103], v[168:171], v[216:219], v[100:103]
	v_mfma_f32_16x16x32_bf16 v[92:95], v[176:179], v[216:219], v[92:95]
	v_mfma_f32_16x16x32_bf16 v[84:87], v[168:171], v[224:227], v[84:87]
	v_mfma_f32_16x16x32_bf16 v[76:79], v[176:179], v[224:227], v[76:79]
	v_mfma_f32_16x16x32_bf16 v[120:123], v[180:183], v[196:199], 0
	v_mfma_f32_16x16x32_bf16 v[112:115], v[188:191], v[196:199], 0
	v_mfma_f32_16x16x32_bf16 v[104:107], v[180:183], v[204:207], 0
	v_mfma_f32_16x16x32_bf16 v[96:99], v[188:191], v[204:207], 0
	v_mfma_f32_16x16x32_bf16 v[88:91], v[180:183], v[212:215], 0
	v_mfma_f32_16x16x32_bf16 v[80:83], v[188:191], v[212:215], 0
	v_mfma_f32_16x16x32_bf16 v[72:75], v[180:183], v[220:223], 0
	v_mfma_f32_16x16x32_bf16 v[68:71], v[188:191], v[220:223], 0
	v_mfma_f32_16x16x32_bf16 v[120:123], v[184:187], v[200:203], v[120:123]
	v_mfma_f32_16x16x32_bf16 v[112:115], v[192:195], v[200:203], v[112:115]
	v_mfma_f32_16x16x32_bf16 v[104:107], v[184:187], v[208:211], v[104:107]
	v_mfma_f32_16x16x32_bf16 v[96:99], v[192:195], v[208:211], v[96:99]
	v_mfma_f32_16x16x32_bf16 v[88:91], v[184:187], v[216:219], v[88:91]
	v_mfma_f32_16x16x32_bf16 v[80:83], v[192:195], v[216:219], v[80:83]
	v_mfma_f32_16x16x32_bf16 v[72:75], v[184:187], v[224:227], v[72:75]
	v_mfma_f32_16x16x32_bf16 v[68:71], v[192:195], v[224:227], v[68:71]
	s_setprio 0
	s_barrier
	s_add_i32 s43, s50, s10
	s_mov_b32 m0, s43
	ds_read_b128 v[196:199], v167 offset:16384
	ds_read_b128 v[200:203], v167 offset:17408
	ds_read_b128 v[204:207], v167 offset:18432
	ds_read_b128 v[208:211], v167 offset:19456
	ds_read_b128 v[212:215], v167 offset:20480
	ds_read_b128 v[216:219], v167 offset:21504
	ds_read_b128 v[220:223], v167 offset:22528
	ds_read_b128 v[224:227], v167 offset:23552
	global_load_lds_dwordx4 v2, s[46:47]
	s_add_i32 m0, s43, 0x2000
	s_add_u32 s50, s46, 0x80000
	s_addc_u32 s51, s47, 0
	s_add_i32 s33, s33, s10
	global_load_lds_dwordx4 v0, s[46:47]
	s_mov_b32 m0, s33
	s_nop 0
	global_load_lds_dwordx4 v2, s[50:51]
	s_add_i32 m0, s33, 0x2000
	s_nop 0
	global_load_lds_dwordx4 v0, s[50:51]
	s_mov_b32 m0, s12
	s_nop 0
	global_load_lds_dwordx4 v134, s[48:49]
	s_mov_b32 m0, s13
	s_nop 0
	global_load_lds_dwordx4 v132, s[48:49]
	s_cmp_lg_u32 s32, 0
	s_cbranch_scc1 .Lpj_skip2_p
	s_waitcnt vmcnt(8)
.Lpj_skip2_p:
	s_mov_b32 s32, 0
	s_waitcnt lgkmcnt(0)
	s_barrier
	s_setprio 1
	s_waitcnt lgkmcnt(0)
	v_mfma_f32_16x16x32_bf16 v[64:67], v[154:157], v[196:199], 0
	v_mfma_f32_16x16x32_bf16 v[60:63], v[172:175], v[196:199], 0
	v_mfma_f32_16x16x32_bf16 v[52:55], v[154:157], v[204:207], 0
	v_mfma_f32_16x16x32_bf16 v[44:47], v[172:175], v[204:207], 0
	v_mfma_f32_16x16x32_bf16 v[36:39], v[154:157], v[212:215], 0
	v_mfma_f32_16x16x32_bf16 v[28:31], v[172:175], v[212:215], 0
	v_mfma_f32_16x16x32_bf16 v[20:23], v[154:157], v[220:223], 0
	v_mfma_f32_16x16x32_bf16 v[12:15], v[172:175], v[220:223], 0
	v_mfma_f32_16x16x32_bf16 v[64:67], v[168:171], v[200:203], v[64:67]
	v_mfma_f32_16x16x32_bf16 v[60:63], v[176:179], v[200:203], v[60:63]
	v_mfma_f32_16x16x32_bf16 v[52:55], v[168:171], v[208:211], v[52:55]
	v_mfma_f32_16x16x32_bf16 v[44:47], v[176:179], v[208:211], v[44:47]
	v_mfma_f32_16x16x32_bf16 v[36:39], v[168:171], v[216:219], v[36:39]
	v_mfma_f32_16x16x32_bf16 v[28:31], v[176:179], v[216:219], v[28:31]
	v_mfma_f32_16x16x32_bf16 v[20:23], v[168:171], v[224:227], v[20:23]
	v_mfma_f32_16x16x32_bf16 v[12:15], v[176:179], v[224:227], v[12:15]
	v_mfma_f32_16x16x32_bf16 v[56:59], v[180:183], v[196:199], 0
	v_mfma_f32_16x16x32_bf16 v[48:51], v[188:191], v[196:199], 0
	v_mfma_f32_16x16x32_bf16 v[40:43], v[180:183], v[204:207], 0
	v_mfma_f32_16x16x32_bf16 v[32:35], v[188:191], v[204:207], 0
	v_mfma_f32_16x16x32_bf16 v[24:27], v[180:183], v[212:215], 0
	v_mfma_f32_16x16x32_bf16 v[16:19], v[188:191], v[212:215], 0
	v_mfma_f32_16x16x32_bf16 v[8:11], v[180:183], v[220:223], 0
	v_mfma_f32_16x16x32_bf16 v[4:7], v[188:191], v[220:223], 0
	v_mfma_f32_16x16x32_bf16 v[56:59], v[184:187], v[200:203], v[56:59]
	v_mfma_f32_16x16x32_bf16 v[48:51], v[192:195], v[200:203], v[48:51]
	v_mfma_f32_16x16x32_bf16 v[40:43], v[184:187], v[208:211], v[40:43]
	v_mfma_f32_16x16x32_bf16 v[32:35], v[192:195], v[208:211], v[32:35]
	v_mfma_f32_16x16x32_bf16 v[24:27], v[184:187], v[216:219], v[24:27]
	v_mfma_f32_16x16x32_bf16 v[16:19], v[192:195], v[216:219], v[16:19]
	v_mfma_f32_16x16x32_bf16 v[8:11], v[184:187], v[224:227], v[8:11]
	v_mfma_f32_16x16x32_bf16 v[4:7], v[192:195], v[224:227], v[4:7]
	s_setprio 0
	s_barrier
	s_add_i32 s33, 0, 0x18000
	v_add_u32_e32 v144, s33, v149
	s_add_i32 s43, 0, 0x1c000
	ds_read_b128 v[154:157], v144
	ds_read_b128 v[168:171], v144 offset:1024
	ds_read_b128 v[172:175], v144 offset:2048
	ds_read_b128 v[176:179], v144 offset:3072
	v_add_u32_e32 v144, s43, v149
	ds_read_b128 v[180:183], v144
	ds_read_b128 v[184:187], v144 offset:1024
	ds_read_b128 v[188:191], v144 offset:2048
	ds_read_b128 v[192:195], v144 offset:3072
	s_add_u32 s48, s48, 0x80000
	s_addc_u32 s49, s49, 0
	s_mov_b32 m0, s14
	ds_read_b128 v[196:199], v167 offset:32768
	ds_read_b128 v[200:203], v167 offset:33792
	ds_read_b128 v[204:207], v167 offset:34816
	ds_read_b128 v[208:211], v167 offset:35840
	ds_read_b128 v[212:215], v167 offset:36864
	ds_read_b128 v[216:219], v167 offset:37888
	ds_read_b128 v[220:223], v167 offset:38912
	ds_read_b128 v[224:227], v167 offset:39936
	global_load_lds_dwordx4 v134, s[48:49]
	s_mov_b32 m0, s15
	s_nop 0
	global_load_lds_dwordx4 v132, s[48:49]
	s_waitcnt vmcnt(8)
	s_waitcnt lgkmcnt(0)
	s_barrier
	s_setprio 1
	s_waitcnt lgkmcnt(0)
	v_mfma_f32_16x16x32_bf16 v[128:131], v[154:157], v[196:199], v[128:131]
	v_mfma_f32_16x16x32_bf16 v[124:127], v[172:175], v[196:199], v[124:127]
	v_mfma_f32_16x16x32_bf16 v[116:119], v[154:157], v[204:207], v[116:119]
	v_mfma_f32_16x16x32_bf16 v[108:111], v[172:175], v[204:207], v[108:111]
	v_mfma_f32_16x16x32_bf16 v[100:103], v[154:157], v[212:215], v[100:103]
	v_mfma_f32_16x16x32_bf16 v[92:95], v[172:175], v[212:215], v[92:95]
	v_mfma_f32_16x16x32_bf16 v[84:87], v[154:157], v[220:223], v[84:87]
	v_mfma_f32_16x16x32_bf16 v[76:79], v[172:175], v[220:223], v[76:79]
	v_mfma_f32_16x16x32_bf16 v[128:131], v[168:171], v[200:203], v[128:131]
	v_mfma_f32_16x16x32_bf16 v[124:127], v[176:179], v[200:203], v[124:127]
	v_mfma_f32_16x16x32_bf16 v[116:119], v[168:171], v[208:211], v[116:119]
	v_mfma_f32_16x16x32_bf16 v[108:111], v[176:179], v[208:211], v[108:111]
	v_mfma_f32_16x16x32_bf16 v[100:103], v[168:171], v[216:219], v[100:103]
	v_mfma_f32_16x16x32_bf16 v[92:95], v[176:179], v[216:219], v[92:95]
	v_mfma_f32_16x16x32_bf16 v[84:87], v[168:171], v[224:227], v[84:87]
	v_mfma_f32_16x16x32_bf16 v[76:79], v[176:179], v[224:227], v[76:79]
	v_mfma_f32_16x16x32_bf16 v[120:123], v[180:183], v[196:199], v[120:123]
	v_mfma_f32_16x16x32_bf16 v[112:115], v[188:191], v[196:199], v[112:115]
	v_mfma_f32_16x16x32_bf16 v[104:107], v[180:183], v[204:207], v[104:107]
	v_mfma_f32_16x16x32_bf16 v[96:99], v[188:191], v[204:207], v[96:99]
	v_mfma_f32_16x16x32_bf16 v[88:91], v[180:183], v[212:215], v[88:91]
	v_mfma_f32_16x16x32_bf16 v[80:83], v[188:191], v[212:215], v[80:83]
	v_mfma_f32_16x16x32_bf16 v[72:75], v[180:183], v[220:223], v[72:75]
	v_mfma_f32_16x16x32_bf16 v[68:71], v[188:191], v[220:223], v[68:71]
	v_mfma_f32_16x16x32_bf16 v[120:123], v[184:187], v[200:203], v[120:123]
	v_mfma_f32_16x16x32_bf16 v[112:115], v[192:195], v[200:203], v[112:115]
	v_mfma_f32_16x16x32_bf16 v[104:107], v[184:187], v[208:211], v[104:107]
	v_mfma_f32_16x16x32_bf16 v[96:99], v[192:195], v[208:211], v[96:99]
	v_mfma_f32_16x16x32_bf16 v[88:91], v[184:187], v[216:219], v[88:91]
	v_mfma_f32_16x16x32_bf16 v[80:83], v[192:195], v[216:219], v[80:83]
	v_mfma_f32_16x16x32_bf16 v[72:75], v[184:187], v[224:227], v[72:75]
	v_mfma_f32_16x16x32_bf16 v[68:71], v[192:195], v[224:227], v[68:71]
	s_setprio 0
	s_barrier
	s_add_i32 s33, s33, s10
	s_mov_b32 m0, s33
	ds_read_b128 v[196:199], v167 offset:49152
	ds_read_b128 v[200:203], v167 offset:50176
	ds_read_b128 v[204:207], v167 offset:51200
	ds_read_b128 v[208:211], v167 offset:52224
	ds_read_b128 v[212:215], v167 offset:53248
	ds_read_b128 v[216:219], v167 offset:54272
	ds_read_b128 v[220:223], v167 offset:55296
	ds_read_b128 v[224:227], v167 offset:56320
	s_add_u32 s100, s46, 0x80
	s_addc_u32 s101, s47, 0
	global_load_lds_dwordx4 v2, s[100:101]
	s_add_i32 m0, s33, 0x2000
	s_add_u32 s46, s46, 0x80080
	s_addc_u32 s47, s47, 0
	s_add_i32 s33, s43, s10
	s_add_u32 s100, s46, 0xfff80000
	s_addc_u32 s101, s47, -1
	global_load_lds_dwordx4 v0, s[100:101]
	s_mov_b32 m0, s33
	s_nop 0
	global_load_lds_dwordx4 v2, s[46:47]
	s_add_i32 m0, s33, 0x2000
	s_nop 0
	global_load_lds_dwordx4 v0, s[46:47]
	s_mov_b32 m0, s16
	s_nop 0
	s_add_u32 s100, s48, 0xfff80080
	s_addc_u32 s101, s49, -1
	global_load_lds_dwordx4 v134, s[100:101]
	s_mov_b32 m0, s17
	s_nop 0
	s_add_u32 s100, s48, 0xfff80080
	s_addc_u32 s101, s49, -1
	global_load_lds_dwordx4 v132, s[100:101]
	s_waitcnt vmcnt(8)
	s_waitcnt lgkmcnt(0)
	s_barrier
	s_setprio 1
	s_waitcnt lgkmcnt(0)
	v_mfma_f32_16x16x32_bf16 v[64:67], v[154:157], v[196:199], v[64:67]
	v_mfma_f32_16x16x32_bf16 v[60:63], v[172:175], v[196:199], v[60:63]
	v_mfma_f32_16x16x32_bf16 v[52:55], v[154:157], v[204:207], v[52:55]
	v_mfma_f32_16x16x32_bf16 v[44:47], v[172:175], v[204:207], v[44:47]
	v_mfma_f32_16x16x32_bf16 v[36:39], v[154:157], v[212:215], v[36:39]
	v_mfma_f32_16x16x32_bf16 v[28:31], v[172:175], v[212:215], v[28:31]
	v_mfma_f32_16x16x32_bf16 v[20:23], v[154:157], v[220:223], v[20:23]
	v_mfma_f32_16x16x32_bf16 v[12:15], v[172:175], v[220:223], v[12:15]
	v_mfma_f32_16x16x32_bf16 v[64:67], v[168:171], v[200:203], v[64:67]
	v_mfma_f32_16x16x32_bf16 v[60:63], v[176:179], v[200:203], v[60:63]
	v_mfma_f32_16x16x32_bf16 v[52:55], v[168:171], v[208:211], v[52:55]
	v_mfma_f32_16x16x32_bf16 v[44:47], v[176:179], v[208:211], v[44:47]
	v_mfma_f32_16x16x32_bf16 v[36:39], v[168:171], v[216:219], v[36:39]
	v_mfma_f32_16x16x32_bf16 v[28:31], v[176:179], v[216:219], v[28:31]
	v_mfma_f32_16x16x32_bf16 v[20:23], v[168:171], v[224:227], v[20:23]
	v_mfma_f32_16x16x32_bf16 v[12:15], v[176:179], v[224:227], v[12:15]
	v_mfma_f32_16x16x32_bf16 v[56:59], v[180:183], v[196:199], v[56:59]
	v_mfma_f32_16x16x32_bf16 v[48:51], v[188:191], v[196:199], v[48:51]
	v_mfma_f32_16x16x32_bf16 v[40:43], v[180:183], v[204:207], v[40:43]
	v_mfma_f32_16x16x32_bf16 v[32:35], v[188:191], v[204:207], v[32:35]
	v_mfma_f32_16x16x32_bf16 v[24:27], v[180:183], v[212:215], v[24:27]
	v_mfma_f32_16x16x32_bf16 v[16:19], v[188:191], v[212:215], v[16:19]
	v_mfma_f32_16x16x32_bf16 v[8:11], v[180:183], v[220:223], v[8:11]
	v_mfma_f32_16x16x32_bf16 v[4:7], v[188:191], v[220:223], v[4:7]
	v_mfma_f32_16x16x32_bf16 v[56:59], v[184:187], v[200:203], v[56:59]
	v_mfma_f32_16x16x32_bf16 v[48:51], v[192:195], v[200:203], v[48:51]
	v_mfma_f32_16x16x32_bf16 v[40:43], v[184:187], v[208:211], v[40:43]
	v_mfma_f32_16x16x32_bf16 v[32:35], v[192:195], v[208:211], v[32:35]
	v_mfma_f32_16x16x32_bf16 v[24:27], v[184:187], v[216:219], v[24:27]
	v_mfma_f32_16x16x32_bf16 v[16:19], v[192:195], v[216:219], v[16:19]
	v_mfma_f32_16x16x32_bf16 v[8:11], v[184:187], v[224:227], v[8:11]
	v_mfma_f32_16x16x32_bf16 v[4:7], v[192:195], v[224:227], v[4:7]
	s_setprio 0
	s_barrier
	s_add_i32 s35, s35, 2
	s_add_u32 s31, s31, 0x100
	s_addc_u32 s34, s34, 0
	s_add_u32 s44, s44, 0x100
	s_addc_u32 s45, s45, 0
	s_cmp_gt_u32 s35, 29

.LBB0_1065:
	s_ashr_i32 s27, s26, 31
	s_lshl_b64 s[6:7], s[26:27], 20
	s_add_u32 s38, s52, s6
	s_addc_u32 s39, s53, s7
	s_and_b64 s[6:7], s[36:37], exec
	s_cselect_b32 s5, s39, s47
	s_cselect_b32 s6, s38, s46
	s_ashr_i32 s25, s24, 31
	s_lshl_b64 s[8:9], s[24:25], 20
	s_add_u32 s40, s54, s8
	s_addc_u32 s41, s55, s9
	s_and_b64 s[8:9], s[36:37], exec
	s_cselect_b32 s7, s41, s45
	s_cselect_b32 s8, s40, s44
	s_add_u32 s9, s44, 0x100
	s_addc_u32 s10, s45, 0
	s_add_u32 s44, s46, 0x80080
	s_addc_u32 s45, s47, 0
	s_mov_b32 s11, -2
	s_add_u32 s12, s44, 0xfff80080
	s_addc_u32 s13, s45, -1
	s_add_i32 s14, 0, 0x10000
	s_cmp_eq_u32 s11, 28
	s_cselect_b32 s49, s5, s13
	s_cselect_b32 s48, s6, s12
	s_cselect_b32 s47, s7, s10
	s_cselect_b32 s46, s8, s9
	s_add_i32 s15, 0, 0x14000
	v_add_u32_e32 v154, s14, v163
	v_add_u32_e32 v158, s15, v163
	ds_read_b128 v[142:145], v154
	ds_read_b128 v[146:149], v154 offset:1024
	ds_read_b128 v[150:153], v154 offset:2048
	ds_read_b128 v[154:157], v154 offset:3072
	ds_read_b128 v[168:171], v158
	ds_read_b128 v[172:175], v158 offset:1024
	ds_read_b128 v[176:179], v158 offset:2048
	ds_read_b128 v[180:183], v158 offset:3072
	s_add_i32 m0, s60, 0xc000
	ds_read_b128 v[184:187], v167
	ds_read_b128 v[188:191], v167 offset:1024
	ds_read_b128 v[192:195], v167 offset:2048
	ds_read_b128 v[196:199], v167 offset:3072
	ds_read_b128 v[200:203], v167 offset:4096
	ds_read_b128 v[204:207], v167 offset:5120
	ds_read_b128 v[208:211], v167 offset:6144
	ds_read_b128 v[212:215], v167 offset:7168
	global_load_lds_dwordx4 v140, s[44:45]
	s_add_i32 m0, s60, 0xe000
	s_nop 0
	global_load_lds_dwordx4 v138, s[44:45]
	s_cmp_lg_u32 s32, 0
	s_cbranch_scc1 .Lgu_skip1_p
	s_waitcnt vmcnt(8)
.Lgu_skip1_p:
	s_waitcnt lgkmcnt(0)
	s_barrier
	s_setprio 1
	s_waitcnt lgkmcnt(0)
	v_mfma_f32_16x16x32_bf16 v[124:127], v[142:145], v[184:187], 0
	v_mfma_f32_16x16x32_bf16 v[120:123], v[150:153], v[184:187], 0
	v_mfma_f32_16x16x32_bf16 v[112:115], v[142:145], v[192:195], 0
	v_mfma_f32_16x16x32_bf16 v[104:107], v[150:153], v[192:195], 0
	v_mfma_f32_16x16x32_bf16 v[96:99], v[142:145], v[200:203], 0
	v_mfma_f32_16x16x32_bf16 v[88:91], v[150:153], v[200:203], 0
	v_mfma_f32_16x16x32_bf16 v[80:83], v[142:145], v[208:211], 0
	v_mfma_f32_16x16x32_bf16 v[72:75], v[150:153], v[208:211], 0
	v_mfma_f32_16x16x32_bf16 v[124:127], v[146:149], v[188:191], v[124:127]
	v_mfma_f32_16x16x32_bf16 v[120:123], v[154:157], v[188:191], v[120:123]
	v_mfma_f32_16x16x32_bf16 v[112:115], v[146:149], v[196:199], v[112:115]
	v_mfma_f32_16x16x32_bf16 v[104:107], v[154:157], v[196:199], v[104:107]
	v_mfma_f32_16x16x32_bf16 v[96:99], v[146:149], v[204:207], v[96:99]
	v_mfma_f32_16x16x32_bf16 v[88:91], v[154:157], v[204:207], v[88:91]
	v_mfma_f32_16x16x32_bf16 v[80:83], v[146:149], v[212:215], v[80:83]
	v_mfma_f32_16x16x32_bf16 v[72:75], v[154:157], v[212:215], v[72:75]
	v_mfma_f32_16x16x32_bf16 v[128:131], v[168:171], v[184:187], 0
	v_mfma_f32_16x16x32_bf16 v[116:119], v[176:179], v[184:187], 0
	v_mfma_f32_16x16x32_bf16 v[108:111], v[168:171], v[192:195], 0
	v_mfma_f32_16x16x32_bf16 v[100:103], v[176:179], v[192:195], 0
	v_mfma_f32_16x16x32_bf16 v[92:95], v[168:171], v[200:203], 0
	v_mfma_f32_16x16x32_bf16 v[84:87], v[176:179], v[200:203], 0
	v_mfma_f32_16x16x32_bf16 v[76:79], v[168:171], v[208:211], 0
	v_mfma_f32_16x16x32_bf16 v[68:71], v[176:179], v[208:211], 0
	v_mfma_f32_16x16x32_bf16 v[128:131], v[172:175], v[188:191], v[128:131]
	v_mfma_f32_16x16x32_bf16 v[116:119], v[180:183], v[188:191], v[116:119]
	v_mfma_f32_16x16x32_bf16 v[108:111], v[172:175], v[196:199], v[108:111]
	v_mfma_f32_16x16x32_bf16 v[100:103], v[180:183], v[196:199], v[100:103]
	v_mfma_f32_16x16x32_bf16 v[92:95], v[172:175], v[204:207], v[92:95]
	v_mfma_f32_16x16x32_bf16 v[84:87], v[180:183], v[204:207], v[84:87]
	v_mfma_f32_16x16x32_bf16 v[76:79], v[172:175], v[212:215], v[76:79]
	v_mfma_f32_16x16x32_bf16 v[68:71], v[180:183], v[212:215], v[68:71]
	s_setprio 0
	s_barrier
	s_add_i32 s12, s14, s56
	s_mov_b32 m0, s12
	ds_read_b128 v[184:187], v167 offset:16384
	ds_read_b128 v[188:191], v167 offset:17408
	ds_read_b128 v[192:195], v167 offset:18432
	ds_read_b128 v[196:199], v167 offset:19456
	ds_read_b128 v[200:203], v167 offset:20480
	ds_read_b128 v[204:207], v167 offset:21504
	ds_read_b128 v[208:211], v167 offset:22528
	ds_read_b128 v[212:215], v167 offset:23552
	global_load_lds_dwordx4 v2, s[46:47]
	s_add_i32 m0, s12, 0x2000
	s_add_u32 s12, s46, 0x80000
	s_addc_u32 s13, s47, 0
	s_add_i32 s14, s15, s56
	global_load_lds_dwordx4 v0, s[46:47]
	s_mov_b32 m0, s14
	s_nop 0
	global_load_lds_dwordx4 v2, s[12:13]
	s_add_i32 m0, s14, 0x2000
	s_nop 0
	global_load_lds_dwordx4 v0, s[12:13]
	s_mov_b32 m0, s60
	s_nop 0
	global_load_lds_dwordx4 v134, s[48:49]
	s_mov_b32 m0, s61
	s_nop 0
	global_load_lds_dwordx4 v132, s[48:49]
	s_cmp_lg_u32 s32, 0
	s_cbranch_scc1 .Lgu_skip2_p
	s_waitcnt vmcnt(8)
.Lgu_skip2_p:
	s_mov_b32 s32, 0
	s_waitcnt lgkmcnt(0)
	s_barrier
	s_setprio 1
	s_waitcnt lgkmcnt(0)
	v_mfma_f32_16x16x32_bf16 v[64:67], v[142:145], v[184:187], 0
	v_mfma_f32_16x16x32_bf16 v[56:59], v[150:153], v[184:187], 0
	v_mfma_f32_16x16x32_bf16 v[48:51], v[142:145], v[192:195], 0
	v_mfma_f32_16x16x32_bf16 v[40:43], v[150:153], v[192:195], 0
	v_mfma_f32_16x16x32_bf16 v[32:35], v[142:145], v[200:203], 0
	v_mfma_f32_16x16x32_bf16 v[24:27], v[150:153], v[200:203], 0
	v_mfma_f32_16x16x32_bf16 v[16:19], v[142:145], v[208:211], 0
	v_mfma_f32_16x16x32_bf16 v[8:11], v[150:153], v[208:211], 0
	v_mfma_f32_16x16x32_bf16 v[64:67], v[146:149], v[188:191], v[64:67]
	v_mfma_f32_16x16x32_bf16 v[56:59], v[154:157], v[188:191], v[56:59]
	v_mfma_f32_16x16x32_bf16 v[48:51], v[146:149], v[196:199], v[48:51]
	v_mfma_f32_16x16x32_bf16 v[40:43], v[154:157], v[196:199], v[40:43]
	v_mfma_f32_16x16x32_bf16 v[32:35], v[146:149], v[204:207], v[32:35]
	v_mfma_f32_16x16x32_bf16 v[24:27], v[154:157], v[204:207], v[24:27]
	v_mfma_f32_16x16x32_bf16 v[16:19], v[146:149], v[212:215], v[16:19]
	v_mfma_f32_16x16x32_bf16 v[8:11], v[154:157], v[212:215], v[8:11]
	v_mfma_f32_16x16x32_bf16 v[60:63], v[168:171], v[184:187], 0
	v_mfma_f32_16x16x32_bf16 v[52:55], v[176:179], v[184:187], 0
	v_mfma_f32_16x16x32_bf16 v[44:47], v[168:171], v[192:195], 0
	v_mfma_f32_16x16x32_bf16 v[36:39], v[176:179], v[192:195], 0
	v_mfma_f32_16x16x32_bf16 v[28:31], v[168:171], v[200:203], 0
	v_mfma_f32_16x16x32_bf16 v[20:23], v[176:179], v[200:203], 0
	v_mfma_f32_16x16x32_bf16 v[12:15], v[168:171], v[208:211], 0
	v_mfma_f32_16x16x32_bf16 v[4:7], v[176:179], v[208:211], 0
	v_mfma_f32_16x16x32_bf16 v[60:63], v[172:175], v[188:191], v[60:63]
	v_mfma_f32_16x16x32_bf16 v[52:55], v[180:183], v[188:191], v[52:55]
	v_mfma_f32_16x16x32_bf16 v[44:47], v[172:175], v[196:199], v[44:47]
	v_mfma_f32_16x16x32_bf16 v[36:39], v[180:183], v[196:199], v[36:39]
	v_mfma_f32_16x16x32_bf16 v[28:31], v[172:175], v[204:207], v[28:31]
	v_mfma_f32_16x16x32_bf16 v[20:23], v[180:183], v[204:207], v[20:23]
	v_mfma_f32_16x16x32_bf16 v[12:15], v[172:175], v[212:215], v[12:15]
	v_mfma_f32_16x16x32_bf16 v[4:7], v[180:183], v[212:215], v[4:7]
	s_setprio 0
	s_barrier
	s_add_i32 s14, 0, 0x18000
	s_add_i32 s15, 0, 0x1c000
	v_add_u32_e32 v154, s14, v163
	v_add_u32_e32 v160, s15, v163
	ds_read_b128 v[142:145], v154
	ds_read_b128 v[146:149], v154 offset:1024
	ds_read_b128 v[150:153], v154 offset:2048
	ds_read_b128 v[154:157], v154 offset:3072
	ds_read_b128 v[168:171], v160
	ds_read_b128 v[172:175], v160 offset:1024
	ds_read_b128 v[176:179], v160 offset:2048
	ds_read_b128 v[180:183], v160 offset:3072
	s_add_u32 s12, s48, 0x80000
	s_addc_u32 s13, s49, 0
	s_mov_b32 m0, s62
	ds_read_b128 v[184:187], v167 offset:32768
	ds_read_b128 v[188:191], v167 offset:33792
	ds_read_b128 v[192:195], v167 offset:34816
	ds_read_b128 v[196:199], v167 offset:35840
	ds_read_b128 v[200:203], v167 offset:36864
	ds_read_b128 v[204:207], v167 offset:37888
	ds_read_b128 v[208:211], v167 offset:38912
	ds_read_b128 v[212:215], v167 offset:39936
	global_load_lds_dwordx4 v134, s[12:13]
	s_mov_b32 m0, s63
	s_nop 0
	global_load_lds_dwordx4 v132, s[12:13]
	s_waitcnt vmcnt(8)
	s_waitcnt lgkmcnt(0)
	s_barrier
	s_setprio 1
	s_waitcnt lgkmcnt(0)
	v_mfma_f32_16x16x32_bf16 v[124:127], v[142:145], v[184:187], v[124:127]
	v_mfma_f32_16x16x32_bf16 v[120:123], v[150:153], v[184:187], v[120:123]
	v_mfma_f32_16x16x32_bf16 v[112:115], v[142:145], v[192:195], v[112:115]
	v_mfma_f32_16x16x32_bf16 v[104:107], v[150:153], v[192:195], v[104:107]
	v_mfma_f32_16x16x32_bf16 v[96:99], v[142:145], v[200:203], v[96:99]
	v_mfma_f32_16x16x32_bf16 v[88:91], v[150:153], v[200:203], v[88:91]
	v_mfma_f32_16x16x32_bf16 v[80:83], v[142:145], v[208:211], v[80:83]
	v_mfma_f32_16x16x32_bf16 v[72:75], v[150:153], v[208:211], v[72:75]
	v_mfma_f32_16x16x32_bf16 v[124:127], v[146:149], v[188:191], v[124:127]
	v_mfma_f32_16x16x32_bf16 v[120:123], v[154:157], v[188:191], v[120:123]
	v_mfma_f32_16x16x32_bf16 v[112:115], v[146:149], v[196:199], v[112:115]
	v_mfma_f32_16x16x32_bf16 v[104:107], v[154:157], v[196:199], v[104:107]
	v_mfma_f32_16x16x32_bf16 v[96:99], v[146:149], v[204:207], v[96:99]
	v_mfma_f32_16x16x32_bf16 v[88:91], v[154:157], v[204:207], v[88:91]
	v_mfma_f32_16x16x32_bf16 v[80:83], v[146:149], v[212:215], v[80:83]
	v_mfma_f32_16x16x32_bf16 v[72:75], v[154:157], v[212:215], v[72:75]
	v_mfma_f32_16x16x32_bf16 v[128:131], v[168:171], v[184:187], v[128:131]
	v_mfma_f32_16x16x32_bf16 v[116:119], v[176:179], v[184:187], v[116:119]
	v_mfma_f32_16x16x32_bf16 v[108:111], v[168:171], v[192:195], v[108:111]
	v_mfma_f32_16x16x32_bf16 v[100:103], v[176:179], v[192:195], v[100:103]
	v_mfma_f32_16x16x32_bf16 v[92:95], v[168:171], v[200:203], v[92:95]
	v_mfma_f32_16x16x32_bf16 v[84:87], v[176:179], v[200:203], v[84:87]
	v_mfma_f32_16x16x32_bf16 v[76:79], v[168:171], v[208:211], v[76:79]
	v_mfma_f32_16x16x32_bf16 v[68:71], v[176:179], v[208:211], v[68:71]
	v_mfma_f32_16x16x32_bf16 v[128:131], v[172:175], v[188:191], v[128:131]
	v_mfma_f32_16x16x32_bf16 v[116:119], v[180:183], v[188:191], v[116:119]
	v_mfma_f32_16x16x32_bf16 v[108:111], v[172:175], v[196:199], v[108:111]
	v_mfma_f32_16x16x32_bf16 v[100:103], v[180:183], v[196:199], v[100:103]
	v_mfma_f32_16x16x32_bf16 v[92:95], v[172:175], v[204:207], v[92:95]
	v_mfma_f32_16x16x32_bf16 v[84:87], v[180:183], v[204:207], v[84:87]
	v_mfma_f32_16x16x32_bf16 v[76:79], v[172:175], v[212:215], v[76:79]
	v_mfma_f32_16x16x32_bf16 v[68:71], v[180:183], v[212:215], v[68:71]
	s_setprio 0
	s_barrier
	s_add_i32 s12, s14, s56
	s_mov_b32 m0, s12
	ds_read_b128 v[184:187], v167 offset:49152
	ds_read_b128 v[188:191], v167 offset:50176
	ds_read_b128 v[192:195], v167 offset:51200
	ds_read_b128 v[196:199], v167 offset:52224
	ds_read_b128 v[200:203], v167 offset:53248
	ds_read_b128 v[204:207], v167 offset:54272
	ds_read_b128 v[208:211], v167 offset:55296
	ds_read_b128 v[212:215], v167 offset:56320
	s_add_u32 s100, s46, 0x80
	s_addc_u32 s101, s47, 0
	global_load_lds_dwordx4 v2, s[100:101]
	s_add_i32 m0, s12, 0x2000
	s_add_u32 s12, s46, 0x80080
	s_addc_u32 s13, s47, 0
	s_add_i32 s14, s15, s56
	s_add_u32 s100, s46, 0x80
	s_addc_u32 s101, s47, 0
	global_load_lds_dwordx4 v0, s[100:101]
	s_mov_b32 m0, s14
	s_nop 0
	global_load_lds_dwordx4 v2, s[12:13]
	s_add_i32 m0, s14, 0x2000
	s_nop 0
	global_load_lds_dwordx4 v0, s[12:13]
	s_mov_b32 m0, s64
	s_nop 0
	s_add_u32 s100, s48, 0x80
	s_addc_u32 s101, s49, 0
	global_load_lds_dwordx4 v134, s[100:101]
	s_mov_b32 m0, s65
	s_nop 0
	s_add_u32 s100, s48, 0x80
	s_addc_u32 s101, s49, 0
	global_load_lds_dwordx4 v132, s[100:101]
	s_waitcnt vmcnt(8)
	s_waitcnt lgkmcnt(0)
	s_barrier
	s_setprio 1
	s_waitcnt lgkmcnt(0)
	v_mfma_f32_16x16x32_bf16 v[64:67], v[142:145], v[184:187], v[64:67]
	v_mfma_f32_16x16x32_bf16 v[56:59], v[150:153], v[184:187], v[56:59]
	v_mfma_f32_16x16x32_bf16 v[48:51], v[142:145], v[192:195], v[48:51]
	v_mfma_f32_16x16x32_bf16 v[40:43], v[150:153], v[192:195], v[40:43]
	v_mfma_f32_16x16x32_bf16 v[32:35], v[142:145], v[200:203], v[32:35]
	v_mfma_f32_16x16x32_bf16 v[24:27], v[150:153], v[200:203], v[24:27]
	v_mfma_f32_16x16x32_bf16 v[16:19], v[142:145], v[208:211], v[16:19]
	v_mfma_f32_16x16x32_bf16 v[8:11], v[150:153], v[208:211], v[8:11]
	v_mfma_f32_16x16x32_bf16 v[64:67], v[146:149], v[188:191], v[64:67]
	v_mfma_f32_16x16x32_bf16 v[56:59], v[154:157], v[188:191], v[56:59]
	v_mfma_f32_16x16x32_bf16 v[48:51], v[146:149], v[196:199], v[48:51]
	v_mfma_f32_16x16x32_bf16 v[40:43], v[154:157], v[196:199], v[40:43]
	v_mfma_f32_16x16x32_bf16 v[32:35], v[146:149], v[204:207], v[32:35]
	v_mfma_f32_16x16x32_bf16 v[24:27], v[154:157], v[204:207], v[24:27]
	v_mfma_f32_16x16x32_bf16 v[16:19], v[146:149], v[212:215], v[16:19]
	v_mfma_f32_16x16x32_bf16 v[8:11], v[154:157], v[212:215], v[8:11]
	v_mfma_f32_16x16x32_bf16 v[60:63], v[168:171], v[184:187], v[60:63]
	v_mfma_f32_16x16x32_bf16 v[52:55], v[176:179], v[184:187], v[52:55]
	v_mfma_f32_16x16x32_bf16 v[44:47], v[168:171], v[192:195], v[44:47]
	v_mfma_f32_16x16x32_bf16 v[36:39], v[176:179], v[192:195], v[36:39]
	v_mfma_f32_16x16x32_bf16 v[28:31], v[168:171], v[200:203], v[28:31]
	v_mfma_f32_16x16x32_bf16 v[20:23], v[176:179], v[200:203], v[20:23]
	v_mfma_f32_16x16x32_bf16 v[12:15], v[168:171], v[208:211], v[12:15]
	v_mfma_f32_16x16x32_bf16 v[4:7], v[176:179], v[208:211], v[4:7]
	v_mfma_f32_16x16x32_bf16 v[60:63], v[172:175], v[188:191], v[60:63]
	v_mfma_f32_16x16x32_bf16 v[52:55], v[180:183], v[188:191], v[52:55]
	v_mfma_f32_16x16x32_bf16 v[44:47], v[172:175], v[196:199], v[44:47]
	v_mfma_f32_16x16x32_bf16 v[36:39], v[180:183], v[196:199], v[36:39]
	v_mfma_f32_16x16x32_bf16 v[28:31], v[172:175], v[204:207], v[28:31]
	v_mfma_f32_16x16x32_bf16 v[20:23], v[180:183], v[204:207], v[20:23]
	v_mfma_f32_16x16x32_bf16 v[12:15], v[172:175], v[212:215], v[12:15]
	v_mfma_f32_16x16x32_bf16 v[4:7], v[180:183], v[212:215], v[4:7]
	s_setprio 0
	s_barrier
	s_add_i32 s11, s11, 2
	s_add_u32 s9, s9, 0x100
	s_addc_u32 s10, s10, 0
	s_add_u32 s44, s44, 0x100
	s_addc_u32 s45, s45, 0
	s_cmp_gt_u32 s11, 29
